# cand28 + collective guard (hardware XCC id == blockIdx%8 for every workgroup, grid 256) deciding local vs global release at the three seams
# baseline (speedup 1.0000x reference)
; #define LAS __attribute__((address_space(3)))
; __device__ __forceinline__ unsigned xb_add(unsigned* p, unsigned v) { return __hip_atomic_fetch_add(p, v, __ATOMIC_RELAXED, __HIP_MEMORY_SCOPE_AGENT); }
; __device__ __forceinline__ unsigned xb_xcc_id() { return (unsigned)__builtin_amdgcn_s_getreg((3 << 11) | 20) & 0xFu; }
; __device__ __forceinline__ XcdBarrier xcd_barrier_post(unsigned* bar, volatile LAS unsigned* st) {
;     XcdBarrier b; b.bar = bar; b.x = xb_xcc_id(); b.st = st;
;     if (threadIdx.x == 0) (void)xb_add(&bar[XB_XCNT(b.x)], 1u);
;     return b;
; __global__ void __launch_bounds__(NWAVES * 64, 2) skel_fwd(Args args) {
;     extern __shared__ __attribute__((aligned(16))) unsigned char lds[];
;     Frame F;
;     F.lds = (LAS unsigned char*)lds;
;     F.MISC = (volatile LAS unsigned*)(F.lds + MISC_OFF);
;     F.tid = threadIdx.x; F.lane = F.tid & 63; F.wave = __builtin_amdgcn_readfirstlane(F.tid >> 6);
;     F.G = gridDim.x; { const int bx = blockIdx.x; F.vcu = (F.G % 8 == 0) ? (bx % 8) * (F.G / 8) + bx / 8 : bx; }
;     unsigned char* ws = args.ws; F.ws = ws; F.out = args.out;
;     F.ctl = (gu32*)(ws + WS_CTL);
;     for (int u = F.tid; u < (LDS_BYTES - LDSCTL_OFF) / 4; u += NWAVES * 64) ((LAS unsigned*)(F.lds + LDSCTL_OFF))[u] = 0u;
;     __syncthreads();
;     XcdBarrier bar; bar.bar = (unsigned*)(F.ctl + CW_BAR); bar.x = 0; bar.st = nullptr;
;     if (!MK_PER_PHASE) bar = xcd_barrier_post((unsigned*)(F.ctl + CW_BAR), F.MISC + 8);
.LBB0_2:
	v_lshl_add_u32 v1, v0, 2, 0
	v_add_u32_e32 v1, 0x20000, v1
	v_mov_b32_e32 v2, 0
	ds_write2st64_b32 v1, v2, v2 offset1:8
	ds_write2st64_b32 v1, v2, v2 offset0:16 offset1:24
	v_or_b32_e32 v1, 0x800, v0
	s_mov_b64 s[2:3], -1
	s_and_saveexec_b64 s[4:5], s[2:3]
	v_lshl_add_u32 v3, v1, 2, 0
	v_add_u32_e32 v3, 0x20000, v3
	ds_write_b32 v3, v2
	s_or_b64 exec, exec, s[4:5]
	s_and_saveexec_b64 s[4:5], s[2:3]
	s_add_i32 s2, 0, 0x20000
	v_lshl_add_u32 v1, v1, 2, s2
	v_mov_b32_e32 v2, 0
	ds_write_b32 v1, v2 offset:2048
	s_or_b64 exec, exec, s[4:5]
	s_load_dwordx2 s[80:81], s[0:1], 0x80
	v_or_b32_e32 v1, 0xc00, v0
	v_cmp_gt_u32_e64 s[2:3], 7, 6
	v_cmp_gt_u32_e64 s[6:7], 7, 5
	s_and_saveexec_b64 s[4:5], s[6:7]
	v_lshl_add_u32 v2, v1, 2, 0
	v_add_u32_e32 v2, 0x20000, v2
	v_mov_b32_e32 v3, 0
	ds_write_b32 v2, v3
	s_or_b64 exec, exec, s[4:5]
	s_load_dwordx2 s[82:83], s[0:1], 0x88
	s_and_saveexec_b64 s[4:5], s[2:3]
	s_add_i32 s2, 0, 0x20000
	v_lshl_add_u32 v1, v1, 2, s2
	v_mov_b32_e32 v2, 0
	ds_write_b32 v1, v2 offset:2048
	s_or_b64 exec, exec, s[4:5]
	s_load_dwordx16 s[4:19], s[0:1], 0x0
	s_load_dwordx16 s[56:71], s[0:1], 0x40
	s_waitcnt lgkmcnt(0)
	s_barrier
	v_writelane_b32 v243, s4, 2
	s_add_u32 s84, s80, 0x4000
	s_getreg_b32 s0, hwreg(HW_REG_XCC_ID, 0, 4)
	v_writelane_b32 v243, s5, 3
	v_writelane_b32 v243, s6, 4
	v_writelane_b32 v243, s7, 5
	v_writelane_b32 v243, s8, 6
	v_writelane_b32 v243, s9, 7
	v_writelane_b32 v243, s10, 8
	v_writelane_b32 v243, s11, 9
	v_writelane_b32 v243, s12, 10
	v_writelane_b32 v243, s13, 11
	v_writelane_b32 v243, s14, 12
	v_writelane_b32 v243, s15, 13
	v_writelane_b32 v243, s16, 14
	v_writelane_b32 v243, s17, 15
	v_writelane_b32 v243, s18, 16
	s_addc_u32 s85, s81, 0
	s_and_b32 s26, s0, 15
	v_cmp_eq_u32_e64 s[86:87], 0, v0
	v_writelane_b32 v243, s19, 17
	s_and_saveexec_b64 s[0:1], s[86:87]
	s_cbranch_execz .LBB0_13
	s_mov_b64 s[2:3], exec
	v_mbcnt_lo_u32_b32 v1, s2, 0
	v_mbcnt_hi_u32_b32 v1, s3, v1
	v_cmp_eq_u32_e32 vcc, 0, v1
	s_and_b64 s[4:5], exec, vcc
	s_mov_b64 exec, s[4:5]
	s_cbranch_execz .LBB0_13
	s_lshl_b32 s4, s26, 8
	s_bcnt1_i32_b64 s2, s[2:3]
	v_mov_b32_e32 v1, s4
	v_mov_b32_e32 v2, s2
	global_atomic_add v1, v2, s[84:85] offset:1024
	s_xor_b32 s4, s26, s73
	s_and_b32 s4, s4, 7
	s_sub_u32 s5, s76, 0x100
	s_or_b32 s4, s4, s5
	s_cmp_eq_u32 s4, 0
	s_cbranch_scc1 .Lxm_ok
	v_mov_b32_e32 v1, 0xc000
	v_mov_b32_e32 v2, 1
	global_atomic_add v1, v2, s[84:85]
.Lxm_ok:
.LBB0_13:
	s_or_b64 exec, exec, s[0:1]
	s_cmp_lt_i32 s82, 1
	s_cselect_b64 s[0:1], -1, 0
	s_cmp_gt_i32 s83, 0
	s_cselect_b64 s[2:3], -1, 0
	s_and_b64 s[0:1], s[0:1], s[2:3]
	s_andn2_b64 vcc, exec, s[0:1]
	s_cbranch_vccnz .LBB0_84
	v_mov_b32_e32 v10, v0
	s_mov_b32 s0, s78
	s_ashr_i32 s1, s0, 31
	s_lshl_b64 s[2:3], s[0:1], 9
	v_ashrrev_i32_e32 v11, 31, v10
	v_lshl_add_u64 v[6:7], s[2:3], 0, v[10:11]
	s_mov_b64 s[2:3], 0x2c000
	v_readfirstlane_b32 s12, v10
	v_cmp_gt_u64_e32 vcc, s[2:3], v[6:7]
	s_and_saveexec_b64 s[2:3], vcc
	s_cbranch_execz .LBB0_17
	s_ashr_i32 s77, s76, 31
	s_lshl_b64 s[4:5], s[76:77], 9
	s_lshl_b64 s[6:7], s[0:1], 13
	s_add_u32 s6, s80, s6
	s_addc_u32 s7, s81, s7
	v_lshl_add_u64 v[2:3], v[10:11], 4, s[6:7]
	s_mov_b64 s[6:7], 0x40000
	v_lshl_add_u64 v[8:9], v[2:3], 0, s[6:7]
	v_mov_b32_e32 v2, 0
	s_lshl_b64 s[6:7], s[76:77], 13
	s_mov_b64 s[8:9], 0
	v_mov_b32_e32 v3, v2
	v_mov_b32_e32 v4, v2
	v_mov_b32_e32 v5, v2
	s_mov_b64 s[10:11], 0x2bfff

; __device__ __forceinline__ unsigned xb_add(unsigned* p, unsigned v) { return __hip_atomic_fetch_add(p, v, __ATOMIC_RELAXED, __HIP_MEMORY_SCOPE_AGENT); }
; __device__ __forceinline__ void xcd_barrier(const XcdBarrier& b) {
;     ...
;         unsigned nloc = b.st[0], nx = b.st[1];
;         if (nloc == 0u) { xcd_barrier_complete(bar, b.x, nloc, nx); b.st[0] = nloc; b.st[1] = nx; }
;         const unsigned old = xb_add(&bar[XB_XSUB(b.x)], 1u);
;         const unsigned gen = old / nloc;
;         if (old + 1u == (gen + 1u) * nloc) {
.LBB0_592:
	v_readlane_b32 s4, v243, 56
	s_lshl_b32 s4, s4, 2
	s_add_u32 s25, s2, s4
	s_addc_u32 s24, s3, 0
	v_mov_b32_e32 v1, s25
	v_add_co_u32_e32 v6, vcc, 0x1000, v1
	v_mov_b32_e32 v1, s24
	s_nop 0
	v_addc_co_u32_e32 v7, vcc, 0, v1, vcc
	v_mov_b32_e32 v245, 0xc000
	global_load_dword v245, v245, s[2:3] sc1
	flat_atomic_add v3, v[6:7], v217 offset:1024 sc0
	v_cvt_f32_u32_e32 v1, v4
	v_sub_u32_e32 v5, 0, v4
	v_rcp_iflag_f32_e32 v1, v1
	s_nop 0
	v_mul_f32_e32 v1, 0x4f7ffffe, v1
	v_cvt_u32_f32_e32 v1, v1
	v_mul_lo_u32 v5, v5, v1
	v_mul_hi_u32 v5, v1, v5
	v_add_u32_e32 v1, v1, v5
	s_waitcnt vmcnt(0) lgkmcnt(0)
	v_mul_hi_u32 v1, v3, v1
	v_mul_lo_u32 v5, v1, v4
	v_sub_u32_e32 v5, v3, v5
	v_cmp_ge_u32_e32 vcc, v5, v4
	v_add_u32_e32 v6, 1, v1
	v_add_u32_e32 v3, 1, v3
	v_cndmask_b32_e32 v1, v1, v6, vcc
	v_sub_u32_e32 v6, v5, v4
	v_cndmask_b32_e32 v5, v5, v6, vcc
	v_cmp_ge_u32_e32 vcc, v5, v4
	v_add_u32_e32 v5, 1, v1
	s_nop 0
	v_cndmask_b32_e32 v1, v1, v5, vcc
	v_mad_u64_u32 v[4:5], s[4:5], v4, v1, v[4:5]
	v_cmp_ne_u32_e32 vcc, v3, v4
	s_and_saveexec_b64 s[4:5], vcc
	s_xor_b64 s[4:5], exec, s[4:5]
	s_cbranch_execz .LBB0_605
	v_mov_b32_e32 v2, s25
	v_add_co_u32_e32 v2, vcc, 0x2000, v2
	v_mov_b32_e32 v3, s24
	s_nop 0
	v_addc_co_u32_e32 v3, vcc, 0, v3, vcc
	flat_load_dword v2, v[2:3] offset:1024 sc1
	s_add_u32 s8, s25, 0x2400
	s_addc_u32 s9, s24, 0
	s_waitcnt vmcnt(0) lgkmcnt(0)
	v_cmp_eq_u32_e32 vcc, v2, v1
	s_and_saveexec_b64 s[6:7], vcc
	s_cbranch_execz .LBB0_604
	s_mov_b32 s26, 1
	s_mov_b64 s[10:11], 0
	s_branch .LBB0_596

; __device__ __forceinline__ unsigned xb_ld(unsigned* p)              { return __hip_atomic_load(p, __ATOMIC_RELAXED, __HIP_MEMORY_SCOPE_AGENT); }
; __device__ __forceinline__ unsigned xb_add(unsigned* p, unsigned v) { return __hip_atomic_fetch_add(p, v, __ATOMIC_RELAXED, __HIP_MEMORY_SCOPE_AGENT); }
; #define XB_SPIN(cond, bar) do { unsigned _sp = 0; while (cond) { __builtin_amdgcn_s_sleep(1); \
;     if ((++_sp & 255u) == 0u) { if (xb_ld(&(bar)[XB_TMO])) break; if (_sp > XB_SPIN_CAP) { atomicAdd(&(bar)[XB_TMO], 1u); break; } } } } while (0)
; __device__ __forceinline__ void xcd_barrier(const XcdBarrier& b) {
;     ...
;         if (old + 1u == (gen + 1u) * nloc) {
;             __builtin_amdgcn_fence(__ATOMIC_RELEASE, "agent");
;             asm volatile("s_waitcnt vmcnt(0)" ::: "memory");
;             const unsigned og = xb_add(&bar[XB_TOP], 1u);
;             const unsigned tg = og / nx;
;             if (og + 1u == (tg + 1u) * nx) xb_add(&bar[XB_TOPGEN], 1u);
;             else XB_SPIN(xb_ld(&bar[XB_TOPGEN]) == tg, bar);
.LBB0_605:
	s_andn2_saveexec_b64 s[4:5], s[4:5]
	s_cbranch_execz .LBB0_621
	v_cmp_ne_u32_e32 vcc, 0, v245
	s_cbranch_vccnz .Lgl_0
	s_branch .Llb_0
.Lgl_0:
	v_mov_b32_e32 v1, s2
	v_add_co_u32_e32 v4, vcc, 0x3000, v1
	v_mov_b32_e32 v1, s3
	buffer_wbl2 sc1
	s_waitcnt vmcnt(0)
	v_addc_co_u32_e32 v5, vcc, 0, v1, vcc
	flat_atomic_add v3, v[4:5], v217 offset:1024 sc0
	v_cvt_f32_u32_e32 v1, v2
	v_sub_u32_e32 v4, 0, v2
	s_mov_b64 s[8:9], -1
	v_rcp_iflag_f32_e32 v1, v1
	s_nop 0
	v_mul_f32_e32 v1, 0x4f7ffffe, v1
	v_cvt_u32_f32_e32 v1, v1
	v_mul_lo_u32 v4, v4, v1
	v_mul_hi_u32 v4, v1, v4
	v_add_u32_e32 v1, v1, v4
	s_waitcnt vmcnt(0) lgkmcnt(0)
	v_mul_hi_u32 v1, v3, v1
	v_mul_lo_u32 v4, v1, v2
	v_sub_u32_e32 v4, v3, v4
	v_cmp_ge_u32_e32 vcc, v4, v2
	v_add_u32_e32 v5, 1, v1
	s_nop 0
	v_cndmask_b32_e32 v1, v1, v5, vcc
	v_sub_u32_e32 v5, v4, v2
	v_cndmask_b32_e32 v4, v4, v5, vcc
	v_cmp_ge_u32_e32 vcc, v4, v2
	v_add_u32_e32 v4, 1, v1
	s_nop 0
	v_cndmask_b32_e32 v1, v1, v4, vcc
	v_add_u32_e32 v4, 1, v3
	v_mad_u64_u32 v[2:3], s[4:5], v2, v1, v[2:3]
	s_add_u32 s4, s2, 0x3500
	s_addc_u32 s5, s3, 0
	v_cmp_ne_u32_e32 vcc, v4, v2
	v_mov_b64_e32 v[2:3], s[4:5]
	s_and_saveexec_b64 s[6:7], vcc
	s_cbranch_execz .LBB0_618
	v_mov_b64_e32 v[2:3], s[4:5]
	flat_load_dword v2, v[2:3] sc1
	s_mov_b64 s[12:13], 0
	s_waitcnt vmcnt(0) lgkmcnt(0)
	v_cmp_eq_u32_e32 vcc, v2, v1
	s_and_saveexec_b64 s[10:11], vcc
	s_cbranch_execz .LBB0_617
	s_add_u32 s8, s2, 0x200
	s_addc_u32 s9, s3, 0
	s_mov_b32 s22, 1
	s_mov_b64 s[2:3], 0
	s_branch .LBB0_610
